# v13 + one static s_setprio 1 for waves 4-7 during both attention phases (mirror of previous)
# baseline (speedup 1.0000x reference)
; __global__ void __launch_bounds__(NWAVES * 64, 2) mega_fwd(Args args) {
;     ...
;         if (layer == 0) {
;             for (int idx = vcu; idx < 1024 + 4096; idx += G) {
;                 size_t tok0; int head, kvh, qb, NT;
;                 if (idx < 1024) { const int xcd = (idx >> 5) & 7, j = idx & 31, i = idx >> 8; kvh = xcd & 3; const int w = (((xcd >> 2) * 4 + i) << 5) + j; head = kvh * 4 + (w >> 6); qb = w & 63; tok0 = MP; NT = LS / 64; }
;                 else { const int id2 = idx - 1024; const int xcd = (id2 >> 5) & 7, j = id2 & 31, i = id2 >> 8; const int gq = xcd * 16 + i; kvh = gq & 3; head = kvh * 4 + (j >> 3); qb = j & 7; tok0 = (size_t)(gq >> 2) * LP; NT = LP / 64; }
.LBB0_607:
	s_or_b64 exec, exec, s[4:5]
	s_cmpk_gt_i32 s72, 0x13ff
	s_waitcnt lgkmcnt(0)
	s_barrier
	s_cbranch_scc1 .LBB0_647
	v_readfirstlane_b32 s99, v182
	s_nop 3
	s_lshr_b32 s99, s99, 8
	s_cmp_eq_u32 s99, 1
	s_cbranch_scc0 .Lsprio_a0
	s_setprio 1

; __global__ void __launch_bounds__(NWAVES * 64, 2) mega_fwd(Args args) {
;     ...
;             const float s1 = wave_sum(ap->in[19][lane] * ap->in[20][lane]), s2 = wave_sum(ap->in[21][lane] * ap->in[22][lane]);
;             const float lam = expf(s1) - expf(s2) + LAMBDA_INIT1;
;             for (int idx = vcu; idx < 512 + 2048; idx += G) {
.LBB0_1066:
	s_or_b64 exec, exec, s[6:7]
	s_waitcnt lgkmcnt(0)
	s_barrier
	s_load_dwordx8 s[16:23], s[0:1], 0x98
	v_and_b32_e32 v4, 64, v157
	s_waitcnt lgkmcnt(0)
	global_load_dword v0, v156, s[16:17]
	global_load_dword v1, v156, s[18:19]
	global_load_dword v2, v156, s[20:21]
	global_load_dword v3, v156, s[22:23]
	v_xor_b32_e32 v5, 1, v157
	v_add_u32_e32 v4, 64, v4
	v_cmp_lt_i32_e32 vcc, v5, v4
	v_xor_b32_e32 v6, 2, v157
	v_xor_b32_e32 v7, 4, v157
	v_cndmask_b32_e32 v5, v157, v5, vcc
	v_lshlrev_b32_e32 v187, 2, v5
	v_cmp_lt_i32_e32 vcc, v6, v4
	v_xor_b32_e32 v8, 8, v157
	v_xor_b32_e32 v9, 16, v157
	v_cndmask_b32_e32 v6, v157, v6, vcc
	v_lshlrev_b32_e32 v188, 2, v6
	v_cmp_lt_i32_e32 vcc, v7, v4
	v_xor_b32_e32 v10, 32, v157
	s_cmpk_gt_i32 s72, 0x9ff
	s_mov_b32 s17, 0
	s_waitcnt vmcnt(2)
	v_mul_f32_e32 v5, v0, v1
	ds_bpermute_b32 v5, v187, v5
	s_waitcnt vmcnt(0)
	v_mul_f32_e32 v11, v2, v3
	ds_bpermute_b32 v11, v187, v11
	s_waitcnt lgkmcnt(1)
	v_fmac_f32_e32 v5, v0, v1
	ds_bpermute_b32 v0, v188, v5
	s_waitcnt lgkmcnt(1)
	v_fmac_f32_e32 v11, v2, v3
	ds_bpermute_b32 v1, v188, v11
	v_cndmask_b32_e32 v2, v157, v7, vcc
	v_lshlrev_b32_e32 v189, 2, v2
	s_waitcnt lgkmcnt(1)
	v_add_f32_e32 v0, v5, v0
	ds_bpermute_b32 v2, v189, v0
	s_waitcnt lgkmcnt(1)
	v_add_f32_e32 v1, v11, v1
	ds_bpermute_b32 v3, v189, v1
	v_cmp_lt_i32_e32 vcc, v8, v4
	s_waitcnt lgkmcnt(1)
	v_add_f32_e32 v0, v0, v2
	v_cndmask_b32_e32 v5, v157, v8, vcc
	v_lshlrev_b32_e32 v190, 2, v5
	s_waitcnt lgkmcnt(0)
	v_add_f32_e32 v1, v1, v3
	ds_bpermute_b32 v2, v190, v0
	ds_bpermute_b32 v3, v190, v1
	v_cmp_lt_i32_e32 vcc, v9, v4
	s_waitcnt lgkmcnt(1)
	v_add_f32_e32 v0, v0, v2
	v_cndmask_b32_e32 v5, v157, v9, vcc
	v_lshlrev_b32_e32 v183, 2, v5
	s_waitcnt lgkmcnt(0)
	v_add_f32_e32 v1, v1, v3
	ds_bpermute_b32 v2, v183, v0
	ds_bpermute_b32 v3, v183, v1
	v_cmp_lt_i32_e32 vcc, v10, v4
	s_waitcnt lgkmcnt(1)
	v_add_f32_e32 v2, v0, v2
	v_cndmask_b32_e32 v4, v157, v10, vcc
	v_lshlrev_b32_e32 v186, 2, v4
	s_waitcnt lgkmcnt(0)
	v_add_f32_e32 v0, v1, v3
	ds_bpermute_b32 v3, v186, v2
	ds_bpermute_b32 v1, v186, v0
	s_cbranch_scc1 .LBB0_1209
	s_waitcnt lgkmcnt(1)
	v_add_f32_e32 v2, v2, v3
	s_mov_b32 s18, 0x3fb8aa3b
	v_mul_f32_e32 v3, 0x3fb8aa3b, v2
	v_fma_f32 v4, v2, s18, -v3
	v_rndne_f32_e32 v5, v3
	v_fmac_f32_e32 v4, 0x32a5705f, v2
	v_sub_f32_e32 v3, v3, v5
	v_add_f32_e32 v3, v3, v4
	v_exp_f32_e32 v3, v3
	v_cvt_i32_f32_e32 v4, v5
	s_waitcnt lgkmcnt(0)
	v_add_f32_e32 v0, v0, v1
	s_mov_b32 s6, 0xc2ce8ed0
	v_cmp_ngt_f32_e32 vcc, s6, v2
	v_ldexp_f32 v1, v3, v4
	v_mul_f32_e32 v3, 0x3fb8aa3b, v0
	v_fma_f32 v4, v0, s18, -v3
	v_rndne_f32_e32 v5, v3
	v_fmac_f32_e32 v4, 0x32a5705f, v0
	v_sub_f32_e32 v3, v3, v5
	v_add_f32_e32 v3, v3, v4
	v_exp_f32_e32 v3, v3
	v_cvt_i32_f32_e32 v4, v5
	s_mov_b32 s7, 0x42b17218
	v_cndmask_b32_e32 v1, 0, v1, vcc
	v_mov_b32_e32 v5, 0x7f800000
	v_cmp_nlt_f32_e32 vcc, s7, v2
	v_ldexp_f32 v2, v3, v4
	s_load_dwordx2 s[20:21], s[0:1], 0x50
	v_cndmask_b32_e32 v1, v5, v1, vcc
	v_cmp_ngt_f32_e32 vcc, s6, v0
	v_readfirstlane_b32 s99, v182
	s_nop 3
	s_lshr_b32 s99, s99, 8
	s_cmp_eq_u32 s99, 1
	s_cbranch_scc0 .Lsprio_a1
	s_setprio 1
